# K-loop heads aligned to 64 bytes (.p2align 6 before the six loop-top labels)
# speedup vs baseline: 1.0162x; 1.0026x over previous
; template <int MODE  , class Epi, class Sched>
; __device__ __forceinline__ void gemm_phase(LAS unsigned char* lds, const GemmDesc g, const Sched& S, const Epi& E) {
;     ...
;         for (int t = 0; t < nt; t += 2) {
.Lnodb_p1c:
	.p2align 6
